# in-proj epilogue rope: half-rotation via v_permlane32_swap pairs instead of 8 ds_bpermute + LDS wait per half block
# baseline (speedup 1.0000x reference)
.LBB0_256:
	v_mov_b64_e32 v[144:145], v[124:125]
	v_mov_b64_e32 v[140:141], v[128:129]
	s_and_b64 vcc, exec, s[40:41]
	v_mov_b64_e32 v[142:143], v[122:123]
	v_mov_b64_e32 v[138:139], v[126:127]
	s_cbranch_vccnz .LBB0_258
	v_mov_b32_e32 v138, v127
	v_mov_b32_e32 v139, v126
	v_mov_b32_e32 v140, v129
	v_mov_b32_e32 v141, v128
	v_mov_b32_e32 v142, v123
	v_mov_b32_e32 v143, v122
	v_mov_b32_e32 v144, v125
	v_mov_b32_e32 v145, v124
	v_permlane32_swap_b32_e32 v138, v139
	v_permlane32_swap_b32_e32 v140, v141
	v_permlane32_swap_b32_e32 v142, v143
	v_permlane32_swap_b32_e32 v144, v145
	v_permlane32_swap_b32_e32 v139, v138
	v_permlane32_swap_b32_e32 v141, v140
	v_permlane32_swap_b32_e32 v143, v142
	v_permlane32_swap_b32_e32 v145, v144
	v_pk_mul_f32 v[138:139], v[178:179], v[138:139]
	v_pk_mul_f32 v[140:141], v[180:181], v[140:141]
	v_pk_mul_f32 v[142:143], v[176:177], v[142:143]
	v_pk_fma_f32 v[140:141], v[128:129], v[136:137], v[140:141]
	v_pk_mul_f32 v[144:145], v[174:175], v[144:145]
	v_pk_fma_f32 v[138:139], v[126:127], v[134:135], v[138:139]
	v_pk_fma_f32 v[144:145], v[124:125], v[132:133], v[144:145]
	v_pk_fma_f32 v[142:143], v[122:123], v[130:131], v[142:143]

.Lpf_1:
	s_andn2_b64 vcc, exec, s[8:9]
	s_mov_b64 s[8:9], -1
	global_store_dwordx4 v[172:173], v[122:125], off
	s_cbranch_vccnz .LBB0_265
	v_mov_b64_e32 v[128:129], v[116:117]
	v_mov_b64_e32 v[124:125], v[120:121]
	s_and_b64 vcc, exec, s[40:41]
	v_mov_b64_e32 v[126:127], v[114:115]
	v_mov_b64_e32 v[122:123], v[118:119]
	s_cbranch_vccnz .LBB0_264
	v_mov_b32_e32 v122, v119
	v_mov_b32_e32 v123, v118
	v_mov_b32_e32 v124, v121
	v_mov_b32_e32 v125, v120
	v_mov_b32_e32 v126, v115
	v_mov_b32_e32 v127, v114
	v_mov_b32_e32 v128, v117
	v_mov_b32_e32 v129, v116
	v_permlane32_swap_b32_e32 v122, v123
	v_permlane32_swap_b32_e32 v124, v125
	v_permlane32_swap_b32_e32 v126, v127
	v_permlane32_swap_b32_e32 v128, v129
	v_permlane32_swap_b32_e32 v123, v122
	v_permlane32_swap_b32_e32 v125, v124
	v_permlane32_swap_b32_e32 v127, v126
	v_permlane32_swap_b32_e32 v129, v128
	v_pk_mul_f32 v[122:123], v[178:179], v[122:123]
	v_pk_mul_f32 v[124:125], v[180:181], v[124:125]
	v_pk_mul_f32 v[126:127], v[176:177], v[126:127]
	v_pk_fma_f32 v[124:125], v[120:121], v[136:137], v[124:125]
	v_pk_mul_f32 v[128:129], v[174:175], v[128:129]
	v_pk_fma_f32 v[122:123], v[118:119], v[134:135], v[122:123]
	v_pk_fma_f32 v[128:129], v[116:117], v[132:133], v[128:129]
	v_pk_fma_f32 v[126:127], v[114:115], v[130:131], v[126:127]

.LBB0_274:
	v_mov_b64_e32 v[128:129], v[108:109]
	v_mov_b64_e32 v[124:125], v[112:113]
	s_and_b64 vcc, exec, s[40:41]
	v_mov_b64_e32 v[126:127], v[106:107]
	v_mov_b64_e32 v[122:123], v[110:111]
	s_cbranch_vccnz .LBB0_276
	v_mov_b32_e32 v122, v111
	v_mov_b32_e32 v123, v110
	v_mov_b32_e32 v124, v113
	v_mov_b32_e32 v125, v112
	v_mov_b32_e32 v126, v107
	v_mov_b32_e32 v127, v106
	v_mov_b32_e32 v128, v109
	v_mov_b32_e32 v129, v108
	v_permlane32_swap_b32_e32 v122, v123
	v_permlane32_swap_b32_e32 v124, v125
	v_permlane32_swap_b32_e32 v126, v127
	v_permlane32_swap_b32_e32 v128, v129
	v_permlane32_swap_b32_e32 v123, v122
	v_permlane32_swap_b32_e32 v125, v124
	v_permlane32_swap_b32_e32 v127, v126
	v_permlane32_swap_b32_e32 v129, v128
	v_pk_mul_f32 v[122:123], v[136:137], v[122:123]
	v_pk_mul_f32 v[124:125], v[138:139], v[124:125]
	v_pk_mul_f32 v[126:127], v[134:135], v[126:127]
	v_pk_fma_f32 v[124:125], v[112:113], v[120:121], v[124:125]
	v_pk_mul_f32 v[128:129], v[132:133], v[128:129]
	v_pk_fma_f32 v[122:123], v[110:111], v[118:119], v[122:123]
	v_pk_fma_f32 v[128:129], v[108:109], v[116:117], v[128:129]
	v_pk_fma_f32 v[126:127], v[106:107], v[114:115], v[126:127]

.Lpf_2:
	s_and_b64 vcc, exec, s[44:45]
	s_mov_b64 s[8:9], -1
	global_store_dwordx4 v[130:131], v[106:109], off
	s_cbranch_vccnz .LBB0_283
	v_mov_b64_e32 v[112:113], v[100:101]
	v_mov_b64_e32 v[108:109], v[104:105]
	s_and_b64 vcc, exec, s[40:41]
	v_mov_b64_e32 v[110:111], v[98:99]
	v_mov_b64_e32 v[106:107], v[102:103]
	s_cbranch_vccnz .LBB0_282
	v_mov_b32_e32 v106, v103
	v_mov_b32_e32 v107, v102
	v_mov_b32_e32 v108, v105
	v_mov_b32_e32 v109, v104
	v_mov_b32_e32 v110, v99
	v_mov_b32_e32 v111, v98
	v_mov_b32_e32 v112, v101
	v_mov_b32_e32 v113, v100
	v_permlane32_swap_b32_e32 v106, v107
	v_permlane32_swap_b32_e32 v108, v109
	v_permlane32_swap_b32_e32 v110, v111
	v_permlane32_swap_b32_e32 v112, v113
	v_permlane32_swap_b32_e32 v107, v106
	v_permlane32_swap_b32_e32 v109, v108
	v_permlane32_swap_b32_e32 v111, v110
	v_permlane32_swap_b32_e32 v113, v112
	v_pk_mul_f32 v[106:107], v[136:137], v[106:107]
	v_pk_mul_f32 v[108:109], v[138:139], v[108:109]
	v_pk_mul_f32 v[110:111], v[134:135], v[110:111]
	v_pk_fma_f32 v[108:109], v[104:105], v[120:121], v[108:109]
	v_pk_mul_f32 v[112:113], v[132:133], v[112:113]
	v_pk_fma_f32 v[106:107], v[102:103], v[118:119], v[106:107]
	v_pk_fma_f32 v[112:113], v[100:101], v[116:117], v[112:113]
	v_pk_fma_f32 v[110:111], v[98:99], v[114:115], v[110:111]

.LBB0_292:
	v_mov_b64_e32 v[112:113], v[92:93]
	v_mov_b64_e32 v[108:109], v[96:97]
	s_and_b64 vcc, exec, s[40:41]
	v_mov_b64_e32 v[110:111], v[90:91]
	v_mov_b64_e32 v[106:107], v[94:95]
	s_cbranch_vccnz .LBB0_294
	v_mov_b32_e32 v106, v95
	v_mov_b32_e32 v107, v94
	v_mov_b32_e32 v108, v97
	v_mov_b32_e32 v109, v96
	v_mov_b32_e32 v110, v91
	v_mov_b32_e32 v111, v90
	v_mov_b32_e32 v112, v93
	v_mov_b32_e32 v113, v92
	v_permlane32_swap_b32_e32 v106, v107
	v_permlane32_swap_b32_e32 v108, v109
	v_permlane32_swap_b32_e32 v110, v111
	v_permlane32_swap_b32_e32 v112, v113
	v_permlane32_swap_b32_e32 v107, v106
	v_permlane32_swap_b32_e32 v109, v108
	v_permlane32_swap_b32_e32 v111, v110
	v_permlane32_swap_b32_e32 v113, v112
	v_pk_mul_f32 v[106:107], v[120:121], v[106:107]
	v_pk_mul_f32 v[108:109], v[122:123], v[108:109]
	v_pk_mul_f32 v[110:111], v[118:119], v[110:111]
	v_pk_fma_f32 v[108:109], v[96:97], v[104:105], v[108:109]
	v_pk_mul_f32 v[112:113], v[116:117], v[112:113]
	v_pk_fma_f32 v[106:107], v[94:95], v[102:103], v[106:107]
	v_pk_fma_f32 v[112:113], v[92:93], v[100:101], v[112:113]
	v_pk_fma_f32 v[110:111], v[90:91], v[98:99], v[110:111]

.Lpf_3:
	s_and_b64 vcc, exec, s[44:45]
	s_mov_b64 s[8:9], -1
	global_store_dwordx4 v[114:115], v[90:93], off
	s_cbranch_vccnz .LBB0_301
	v_mov_b64_e32 v[96:97], v[84:85]
	v_mov_b64_e32 v[92:93], v[88:89]
	s_and_b64 vcc, exec, s[40:41]
	v_mov_b64_e32 v[94:95], v[82:83]
	v_mov_b64_e32 v[90:91], v[86:87]
	s_cbranch_vccnz .LBB0_300
	v_mov_b32_e32 v90, v87
	v_mov_b32_e32 v91, v86
	v_mov_b32_e32 v92, v89
	v_mov_b32_e32 v93, v88
	v_mov_b32_e32 v94, v83
	v_mov_b32_e32 v95, v82
	v_mov_b32_e32 v96, v85
	v_mov_b32_e32 v97, v84
	v_permlane32_swap_b32_e32 v90, v91
	v_permlane32_swap_b32_e32 v92, v93
	v_permlane32_swap_b32_e32 v94, v95
	v_permlane32_swap_b32_e32 v96, v97
	v_permlane32_swap_b32_e32 v91, v90
	v_permlane32_swap_b32_e32 v93, v92
	v_permlane32_swap_b32_e32 v95, v94
	v_permlane32_swap_b32_e32 v97, v96
	v_pk_mul_f32 v[90:91], v[120:121], v[90:91]
	v_pk_mul_f32 v[92:93], v[122:123], v[92:93]
	v_pk_mul_f32 v[94:95], v[118:119], v[94:95]
	v_pk_fma_f32 v[92:93], v[88:89], v[104:105], v[92:93]
	v_pk_mul_f32 v[96:97], v[116:117], v[96:97]
	v_pk_fma_f32 v[90:91], v[86:87], v[102:103], v[90:91]
	v_pk_fma_f32 v[96:97], v[84:85], v[100:101], v[96:97]
	v_pk_fma_f32 v[94:95], v[82:83], v[98:99], v[94:95]

.LBB0_310:
	v_mov_b64_e32 v[96:97], v[76:77]
	v_mov_b64_e32 v[92:93], v[80:81]
	s_and_b64 vcc, exec, s[40:41]
	v_mov_b64_e32 v[94:95], v[74:75]
	v_mov_b64_e32 v[90:91], v[78:79]
	s_cbranch_vccnz .LBB0_312
	v_mov_b32_e32 v90, v79
	v_mov_b32_e32 v91, v78
	v_mov_b32_e32 v92, v81
	v_mov_b32_e32 v93, v80
	v_mov_b32_e32 v94, v75
	v_mov_b32_e32 v95, v74
	v_mov_b32_e32 v96, v77
	v_mov_b32_e32 v97, v76
	v_permlane32_swap_b32_e32 v90, v91
	v_permlane32_swap_b32_e32 v92, v93
	v_permlane32_swap_b32_e32 v94, v95
	v_permlane32_swap_b32_e32 v96, v97
	v_permlane32_swap_b32_e32 v91, v90
	v_permlane32_swap_b32_e32 v93, v92
	v_permlane32_swap_b32_e32 v95, v94
	v_permlane32_swap_b32_e32 v97, v96
	v_pk_mul_f32 v[90:91], v[104:105], v[90:91]
	v_pk_mul_f32 v[92:93], v[106:107], v[92:93]
	v_pk_mul_f32 v[94:95], v[102:103], v[94:95]
	v_pk_fma_f32 v[92:93], v[80:81], v[88:89], v[92:93]
	v_pk_mul_f32 v[96:97], v[100:101], v[96:97]
	v_pk_fma_f32 v[90:91], v[78:79], v[86:87], v[90:91]
	v_pk_fma_f32 v[96:97], v[76:77], v[84:85], v[96:97]
	v_pk_fma_f32 v[94:95], v[74:75], v[82:83], v[94:95]

.Lpf_4:
	s_and_b64 vcc, exec, s[44:45]
	s_mov_b64 s[8:9], -1
	global_store_dwordx4 v[98:99], v[74:77], off
	s_cbranch_vccnz .LBB0_319
	v_mov_b64_e32 v[80:81], v[68:69]
	v_mov_b64_e32 v[76:77], v[72:73]
	s_and_b64 vcc, exec, s[40:41]
	v_mov_b64_e32 v[78:79], v[66:67]
	v_mov_b64_e32 v[74:75], v[70:71]
	s_cbranch_vccnz .LBB0_318
	v_mov_b32_e32 v74, v71
	v_mov_b32_e32 v75, v70
	v_mov_b32_e32 v76, v73
	v_mov_b32_e32 v77, v72
	v_mov_b32_e32 v78, v67
	v_mov_b32_e32 v79, v66
	v_mov_b32_e32 v80, v69
	v_mov_b32_e32 v81, v68
	v_permlane32_swap_b32_e32 v74, v75
	v_permlane32_swap_b32_e32 v76, v77
	v_permlane32_swap_b32_e32 v78, v79
	v_permlane32_swap_b32_e32 v80, v81
	v_permlane32_swap_b32_e32 v75, v74
	v_permlane32_swap_b32_e32 v77, v76
	v_permlane32_swap_b32_e32 v79, v78
	v_permlane32_swap_b32_e32 v81, v80
	v_pk_mul_f32 v[74:75], v[104:105], v[74:75]
	v_pk_mul_f32 v[76:77], v[106:107], v[76:77]
	v_pk_mul_f32 v[78:79], v[102:103], v[78:79]
	v_pk_fma_f32 v[76:77], v[72:73], v[88:89], v[76:77]
	v_pk_mul_f32 v[80:81], v[100:101], v[80:81]
	v_pk_fma_f32 v[74:75], v[70:71], v[86:87], v[74:75]
	v_pk_fma_f32 v[80:81], v[68:69], v[84:85], v[80:81]
	v_pk_fma_f32 v[78:79], v[66:67], v[82:83], v[78:79]

.LBB0_328:
	v_mov_b64_e32 v[80:81], v[60:61]
	v_mov_b64_e32 v[76:77], v[64:65]
	s_and_b64 vcc, exec, s[40:41]
	v_mov_b64_e32 v[78:79], v[58:59]
	v_mov_b64_e32 v[74:75], v[62:63]
	s_cbranch_vccnz .LBB0_330
	v_mov_b32_e32 v74, v63
	v_mov_b32_e32 v75, v62
	v_mov_b32_e32 v76, v65
	v_mov_b32_e32 v77, v64
	v_mov_b32_e32 v78, v59
	v_mov_b32_e32 v79, v58
	v_mov_b32_e32 v80, v61
	v_mov_b32_e32 v81, v60
	v_permlane32_swap_b32_e32 v74, v75
	v_permlane32_swap_b32_e32 v76, v77
	v_permlane32_swap_b32_e32 v78, v79
	v_permlane32_swap_b32_e32 v80, v81
	v_permlane32_swap_b32_e32 v75, v74
	v_permlane32_swap_b32_e32 v77, v76
	v_permlane32_swap_b32_e32 v79, v78
	v_permlane32_swap_b32_e32 v81, v80
	v_pk_mul_f32 v[74:75], v[88:89], v[74:75]
	v_pk_mul_f32 v[76:77], v[90:91], v[76:77]
	v_pk_mul_f32 v[78:79], v[86:87], v[78:79]
	v_pk_fma_f32 v[76:77], v[64:65], v[72:73], v[76:77]
	v_pk_mul_f32 v[80:81], v[84:85], v[80:81]
	v_pk_fma_f32 v[74:75], v[62:63], v[70:71], v[74:75]
	v_pk_fma_f32 v[80:81], v[60:61], v[68:69], v[80:81]
	v_pk_fma_f32 v[78:79], v[58:59], v[66:67], v[78:79]

.Lpf_5:
	s_and_b64 vcc, exec, s[44:45]
	s_mov_b64 s[8:9], -1
	global_store_dwordx4 v[82:83], v[58:61], off
	s_cbranch_vccnz .LBB0_337
	v_mov_b64_e32 v[64:65], v[52:53]
	v_mov_b64_e32 v[60:61], v[56:57]
	s_and_b64 vcc, exec, s[40:41]
	v_mov_b64_e32 v[62:63], v[50:51]
	v_mov_b64_e32 v[58:59], v[54:55]
	s_cbranch_vccnz .LBB0_336
	v_mov_b32_e32 v58, v55
	v_mov_b32_e32 v59, v54
	v_mov_b32_e32 v60, v57
	v_mov_b32_e32 v61, v56
	v_mov_b32_e32 v62, v51
	v_mov_b32_e32 v63, v50
	v_mov_b32_e32 v64, v53
	v_mov_b32_e32 v65, v52
	v_permlane32_swap_b32_e32 v58, v59
	v_permlane32_swap_b32_e32 v60, v61
	v_permlane32_swap_b32_e32 v62, v63
	v_permlane32_swap_b32_e32 v64, v65
	v_permlane32_swap_b32_e32 v59, v58
	v_permlane32_swap_b32_e32 v61, v60
	v_permlane32_swap_b32_e32 v63, v62
	v_permlane32_swap_b32_e32 v65, v64
	v_pk_mul_f32 v[58:59], v[88:89], v[58:59]
	v_pk_mul_f32 v[60:61], v[90:91], v[60:61]
	v_pk_mul_f32 v[62:63], v[86:87], v[62:63]
	v_pk_fma_f32 v[60:61], v[56:57], v[72:73], v[60:61]
	v_pk_mul_f32 v[64:65], v[84:85], v[64:65]
	v_pk_fma_f32 v[58:59], v[54:55], v[70:71], v[58:59]
	v_pk_fma_f32 v[64:65], v[52:53], v[68:69], v[64:65]
	v_pk_fma_f32 v[62:63], v[50:51], v[66:67], v[62:63]

.LBB0_346:
	v_mov_b64_e32 v[64:65], v[44:45]
	v_mov_b64_e32 v[60:61], v[48:49]
	s_and_b64 vcc, exec, s[40:41]
	v_mov_b64_e32 v[62:63], v[42:43]
	v_mov_b64_e32 v[58:59], v[46:47]
	s_cbranch_vccnz .LBB0_348
	v_mov_b32_e32 v58, v47
	v_mov_b32_e32 v59, v46
	v_mov_b32_e32 v60, v49
	v_mov_b32_e32 v61, v48
	v_mov_b32_e32 v62, v43
	v_mov_b32_e32 v63, v42
	v_mov_b32_e32 v64, v45
	v_mov_b32_e32 v65, v44
	v_permlane32_swap_b32_e32 v58, v59
	v_permlane32_swap_b32_e32 v60, v61
	v_permlane32_swap_b32_e32 v62, v63
	v_permlane32_swap_b32_e32 v64, v65
	v_permlane32_swap_b32_e32 v59, v58
	v_permlane32_swap_b32_e32 v61, v60
	v_permlane32_swap_b32_e32 v63, v62
	v_permlane32_swap_b32_e32 v65, v64
	v_pk_mul_f32 v[58:59], v[72:73], v[58:59]
	v_pk_mul_f32 v[60:61], v[74:75], v[60:61]
	v_pk_mul_f32 v[62:63], v[70:71], v[62:63]
	v_pk_fma_f32 v[60:61], v[48:49], v[56:57], v[60:61]
	v_pk_mul_f32 v[64:65], v[68:69], v[64:65]
	v_pk_fma_f32 v[58:59], v[46:47], v[54:55], v[58:59]
	v_pk_fma_f32 v[64:65], v[44:45], v[52:53], v[64:65]
	v_pk_fma_f32 v[62:63], v[42:43], v[50:51], v[62:63]

.Lpf_6:
	s_and_b64 vcc, exec, s[44:45]
	s_mov_b64 s[8:9], -1
	global_store_dwordx4 v[66:67], v[42:45], off
	s_cbranch_vccnz .LBB0_355
	v_mov_b64_e32 v[48:49], v[36:37]
	v_mov_b64_e32 v[44:45], v[40:41]
	s_and_b64 vcc, exec, s[40:41]
	v_mov_b64_e32 v[46:47], v[34:35]
	v_mov_b64_e32 v[42:43], v[38:39]
	s_cbranch_vccnz .LBB0_354
	v_mov_b32_e32 v42, v39
	v_mov_b32_e32 v43, v38
	v_mov_b32_e32 v44, v41
	v_mov_b32_e32 v45, v40
	v_mov_b32_e32 v46, v35
	v_mov_b32_e32 v47, v34
	v_mov_b32_e32 v48, v37
	v_mov_b32_e32 v49, v36
	v_permlane32_swap_b32_e32 v42, v43
	v_permlane32_swap_b32_e32 v44, v45
	v_permlane32_swap_b32_e32 v46, v47
	v_permlane32_swap_b32_e32 v48, v49
	v_permlane32_swap_b32_e32 v43, v42
	v_permlane32_swap_b32_e32 v45, v44
	v_permlane32_swap_b32_e32 v47, v46
	v_permlane32_swap_b32_e32 v49, v48
	v_pk_mul_f32 v[42:43], v[72:73], v[42:43]
	v_pk_mul_f32 v[44:45], v[74:75], v[44:45]
	v_pk_mul_f32 v[46:47], v[70:71], v[46:47]
	v_pk_fma_f32 v[44:45], v[40:41], v[56:57], v[44:45]
	v_pk_mul_f32 v[48:49], v[68:69], v[48:49]
	v_pk_fma_f32 v[42:43], v[38:39], v[54:55], v[42:43]
	v_pk_fma_f32 v[48:49], v[36:37], v[52:53], v[48:49]
	v_pk_fma_f32 v[46:47], v[34:35], v[50:51], v[46:47]

.LBB0_364:
	v_mov_b64_e32 v[48:49], v[28:29]
	v_mov_b64_e32 v[44:45], v[32:33]
	s_and_b64 vcc, exec, s[40:41]
	v_mov_b64_e32 v[46:47], v[26:27]
	v_mov_b64_e32 v[42:43], v[30:31]
	s_cbranch_vccnz .LBB0_366
	v_mov_b32_e32 v42, v31
	v_mov_b32_e32 v43, v30
	v_mov_b32_e32 v44, v33
	v_mov_b32_e32 v45, v32
	v_mov_b32_e32 v46, v27
	v_mov_b32_e32 v47, v26
	v_mov_b32_e32 v48, v29
	v_mov_b32_e32 v49, v28
	v_permlane32_swap_b32_e32 v42, v43
	v_permlane32_swap_b32_e32 v44, v45
	v_permlane32_swap_b32_e32 v46, v47
	v_permlane32_swap_b32_e32 v48, v49
	v_permlane32_swap_b32_e32 v43, v42
	v_permlane32_swap_b32_e32 v45, v44
	v_permlane32_swap_b32_e32 v47, v46
	v_permlane32_swap_b32_e32 v49, v48
	v_pk_mul_f32 v[42:43], v[56:57], v[42:43]
	v_pk_mul_f32 v[44:45], v[58:59], v[44:45]
	v_pk_mul_f32 v[46:47], v[54:55], v[46:47]
	v_pk_fma_f32 v[44:45], v[32:33], v[40:41], v[44:45]
	v_pk_mul_f32 v[48:49], v[52:53], v[48:49]
	v_pk_fma_f32 v[42:43], v[30:31], v[38:39], v[42:43]
	v_pk_fma_f32 v[48:49], v[28:29], v[36:37], v[48:49]
	v_pk_fma_f32 v[46:47], v[26:27], v[34:35], v[46:47]

.Lpf_7:
	s_and_b64 vcc, exec, s[44:45]
	s_mov_b64 s[8:9], -1
	global_store_dwordx4 v[50:51], v[26:29], off
	s_cbranch_vccnz .LBB0_373
	v_mov_b64_e32 v[32:33], v[20:21]
	v_mov_b64_e32 v[28:29], v[24:25]
	s_and_b64 vcc, exec, s[40:41]
	v_mov_b64_e32 v[30:31], v[18:19]
	v_mov_b64_e32 v[26:27], v[22:23]
	s_cbranch_vccnz .LBB0_372
	v_mov_b32_e32 v26, v23
	v_mov_b32_e32 v27, v22
	v_mov_b32_e32 v28, v25
	v_mov_b32_e32 v29, v24
	v_mov_b32_e32 v30, v19
	v_mov_b32_e32 v31, v18
	v_mov_b32_e32 v32, v21
	v_mov_b32_e32 v33, v20
	v_permlane32_swap_b32_e32 v26, v27
	v_permlane32_swap_b32_e32 v28, v29
	v_permlane32_swap_b32_e32 v30, v31
	v_permlane32_swap_b32_e32 v32, v33
	v_permlane32_swap_b32_e32 v27, v26
	v_permlane32_swap_b32_e32 v29, v28
	v_permlane32_swap_b32_e32 v31, v30
	v_permlane32_swap_b32_e32 v33, v32
	v_pk_mul_f32 v[26:27], v[56:57], v[26:27]
	v_pk_mul_f32 v[28:29], v[58:59], v[28:29]
	v_pk_mul_f32 v[30:31], v[54:55], v[30:31]
	v_pk_fma_f32 v[28:29], v[24:25], v[40:41], v[28:29]
	v_pk_mul_f32 v[32:33], v[52:53], v[32:33]
	v_pk_fma_f32 v[26:27], v[22:23], v[38:39], v[26:27]
	v_pk_fma_f32 v[32:33], v[20:21], v[36:37], v[32:33]
	v_pk_fma_f32 v[30:31], v[18:19], v[34:35], v[30:31]

.LBB0_382:
	v_mov_b64_e32 v[32:33], v[12:13]
	v_mov_b64_e32 v[28:29], v[16:17]
	s_and_b64 vcc, exec, s[40:41]
	v_mov_b64_e32 v[30:31], v[10:11]
	v_mov_b64_e32 v[26:27], v[14:15]
	s_cbranch_vccnz .LBB0_384
	v_mov_b32_e32 v26, v15
	v_mov_b32_e32 v27, v14
	v_mov_b32_e32 v28, v17
	v_mov_b32_e32 v29, v16
	v_mov_b32_e32 v30, v11
	v_mov_b32_e32 v31, v10
	v_mov_b32_e32 v32, v13
	v_mov_b32_e32 v33, v12
	v_permlane32_swap_b32_e32 v26, v27
	v_permlane32_swap_b32_e32 v28, v29
	v_permlane32_swap_b32_e32 v30, v31
	v_permlane32_swap_b32_e32 v32, v33
	v_permlane32_swap_b32_e32 v27, v26
	v_permlane32_swap_b32_e32 v29, v28
	v_permlane32_swap_b32_e32 v31, v30
	v_permlane32_swap_b32_e32 v33, v32
	v_pk_mul_f32 v[26:27], v[40:41], v[26:27]
	v_pk_mul_f32 v[28:29], v[42:43], v[28:29]
	v_pk_mul_f32 v[30:31], v[38:39], v[30:31]
	v_pk_fma_f32 v[28:29], v[16:17], v[24:25], v[28:29]
	v_pk_mul_f32 v[32:33], v[36:37], v[32:33]
	v_pk_fma_f32 v[26:27], v[14:15], v[22:23], v[26:27]
	v_pk_fma_f32 v[32:33], v[12:13], v[20:21], v[32:33]
	v_pk_fma_f32 v[30:31], v[10:11], v[18:19], v[30:31]

.LBB0_387:
	v_pk_mul_f32 v[10:11], v[28:29], s[94:95] op_sel_hi:[1,0]
	v_pk_mul_f32 v[12:13], v[26:27], s[94:95] op_sel_hi:[1,0]
	v_pk_mul_f32 v[14:15], v[32:33], s[94:95] op_sel_hi:[1,0]
	v_pk_mul_f32 v[16:17], v[30:31], s[94:95] op_sel_hi:[1,0]
	v_cndmask_b32_e64 v0, v28, v10, s[42:43]
	v_cndmask_b32_e64 v11, v29, v11, s[42:43]
	v_cndmask_b32_e64 v10, v26, v12, s[42:43]
	v_cndmask_b32_e64 v12, v27, v13, s[42:43]
	v_cndmask_b32_e64 v13, v32, v14, s[42:43]
	v_cndmask_b32_e64 v14, v33, v15, s[42:43]
	v_cndmask_b32_e64 v15, v30, v16, s[42:43]
	v_cndmask_b32_e64 v16, v31, v17, s[42:43]
	v_cvt_pk_bf16_f32 v10, v10, v12
	v_cvt_pk_bf16_f32 v11, v0, v11
	v_cvt_pk_bf16_f32 v12, v15, v16
	v_cvt_pk_bf16_f32 v13, v13, v14
	s_and_b64 vcc, exec, s[44:45]
	s_mov_b64 s[8:9], -1
	global_store_dwordx4 v[34:35], v[10:13], off
	s_cbranch_vccnz .LBB0_391
	v_mov_b64_e32 v[16:17], v[4:5]
	v_mov_b64_e32 v[12:13], v[8:9]
	s_and_b64 vcc, exec, s[40:41]
	v_mov_b64_e32 v[14:15], v[2:3]
	v_mov_b64_e32 v[10:11], v[6:7]
	s_cbranch_vccnz .LBB0_390
	v_mov_b32_e32 v10, v7
	v_mov_b32_e32 v11, v6
	v_mov_b32_e32 v12, v9
	v_mov_b32_e32 v13, v8
	v_mov_b32_e32 v14, v3
	v_mov_b32_e32 v15, v2
	v_mov_b32_e32 v16, v5
	v_mov_b32_e32 v17, v4
	v_permlane32_swap_b32_e32 v10, v11
	v_permlane32_swap_b32_e32 v12, v13
	v_permlane32_swap_b32_e32 v14, v15
	v_permlane32_swap_b32_e32 v16, v17
	v_permlane32_swap_b32_e32 v11, v10
	v_permlane32_swap_b32_e32 v13, v12
	v_permlane32_swap_b32_e32 v15, v14
	v_permlane32_swap_b32_e32 v17, v16
	v_pk_mul_f32 v[10:11], v[40:41], v[10:11]
	v_pk_mul_f32 v[12:13], v[42:43], v[12:13]
	v_pk_mul_f32 v[14:15], v[38:39], v[14:15]
	v_pk_fma_f32 v[12:13], v[8:9], v[24:25], v[12:13]
	v_pk_mul_f32 v[16:17], v[36:37], v[16:17]
	v_pk_fma_f32 v[10:11], v[6:7], v[22:23], v[10:11]
	v_pk_fma_f32 v[16:17], v[4:5], v[20:21], v[16:17]
	v_pk_fma_f32 v[14:15], v[2:3], v[18:19], v[14:15]
